# EpiResid first half: counted waits per row group (vmcnt 12/14/16/18) instead of one vmcnt(0) after all 16 residual loads
# speedup vs baseline: 1.0051x; 1.0051x over previous
.LBB0_1013:
	v_mov_b32_e32 v128, v179
	s_ashr_i32 s35, s34, 31
	v_readfirstlane_b32 s9, v128
	s_ashr_i32 s8, s9, 8
	s_lshl_b32 s53, s8, 6
	s_bfe_u32 s52, s9, 0x20006
	s_lshl_b64 s[6:7], s[34:35], 8
	s_ashr_i32 s31, s53, 31
	s_add_u32 s6, s6, s53
	s_addc_u32 s7, s7, s31
	s_lshl_b32 s50, s30, 8
	v_and_b32_e32 v215, 15, v128
	s_ashr_i32 s51, s50, 31
	v_readlane_b32 s64, v250, 0
	v_bfe_u32 v216, v128, 4, 2
	v_or_b32_e32 v128, s6, v215
	v_mov_b32_e32 v129, s7
	s_lshl_b32 s31, s52, 5
	s_lshl_b64 s[36:37], s[34:35], 18
	s_lshl_b64 s[6:7], s[50:51], 2
	v_readlane_b32 s70, v250, 6
	v_readlane_b32 s71, v250, 7
	s_add_u32 s6, s70, s6
	s_addc_u32 s7, s71, s7
	s_lshl_b32 s51, s52, 7
	s_add_u32 s6, s6, s51
	s_addc_u32 s7, s7, 0
	v_lshlrev_b32_e32 v176, 5, v216
	v_lshl_add_u64 v[130:131], s[6:7], 0, v[176:177]
	v_lshlrev_b64 v[128:129], 12, v[128:129]
	v_lshl_add_u64 v[200:201], v[130:131], 0, v[128:129]
	global_load_dwordx4 v[218:221], v[200:201], off
	global_load_dwordx4 v[222:225], v[200:201], off offset:16
	global_load_dwordx4 v[226:229], v[200:201], off offset:512
	global_load_dwordx4 v[230:233], v[200:201], off offset:528
	s_mov_b64 s[6:7], 0x10000
	v_lshl_add_u64 v[128:129], v[200:201], 0, s[6:7]
	s_mov_b32 s6, 0x10000
	v_add_co_u32_e32 v130, vcc, s6, v200
	s_mov_b64 s[6:7], 0x10200
	v_lshl_add_u64 v[132:133], v[200:201], 0, s[6:7]
	s_mov_b64 s[6:7], 0x20000
	v_addc_co_u32_e32 v131, vcc, 0, v201, vcc
	v_lshl_add_u64 v[134:135], v[200:201], 0, s[6:7]
	s_mov_b32 s6, 0x20000
	v_add_co_u32_e32 v136, vcc, s6, v200
	s_mov_b64 s[6:7], 0x20200
	v_lshl_add_u64 v[138:139], v[200:201], 0, s[6:7]
	s_mov_b64 s[6:7], 0x30000
	v_addc_co_u32_e32 v137, vcc, 0, v201, vcc
	v_lshl_add_u64 v[196:197], v[200:201], 0, s[6:7]
	s_mov_b32 s6, 0x30000
	v_add_co_u32_e32 v198, vcc, s6, v200
	s_mov_b64 s[6:7], 0x30200
	s_nop 0
	v_addc_co_u32_e32 v199, vcc, 0, v201, vcc
	v_lshl_add_u64 v[234:235], v[200:201], 0, s[6:7]
	global_load_dwordx4 v[172:175], v[130:131], off
	global_load_dwordx4 v[168:171], v[128:129], off offset:16
	global_load_dwordx4 v[164:167], v[130:131], off offset:512
	global_load_dwordx4 v[160:163], v[132:133], off offset:16
	global_load_dwordx4 v[156:159], v[136:137], off
	global_load_dwordx4 v[152:155], v[134:135], off offset:16
	global_load_dwordx4 v[148:151], v[136:137], off offset:512
	global_load_dwordx4 v[144:147], v[138:139], off offset:16
	global_load_dwordx4 v[140:143], v[198:199], off
	s_nop 0
	global_load_dwordx4 v[136:139], v[196:197], off offset:16
	global_load_dwordx4 v[132:135], v[198:199], off offset:512
	global_load_dwordx4 v[128:131], v[234:235], off offset:16
	v_or_b32_e32 v198, s53, v215
	v_ashrrev_i32_e32 v199, 31, v198
	v_lshlrev_b64 v[196:197], 10, v[198:199]
	v_lshl_or_b32 v176, v216, 3, s50
	v_lshl_add_u64 v[234:235], v[196:197], 0, s[36:37]
	v_or_b32_e32 v196, s31, v176
	v_lshl_add_u64 v[236:237], v[234:235], 2, s[70:71]
	v_ashrrev_i32_e32 v197, 31, v196
	v_lshl_add_u64 v[236:237], v[196:197], 2, v[236:237]
	v_cmp_lt_i32_e32 vcc, v209, v204
	v_readlane_b32 s50, v250, 42
	v_readlane_b32 s51, v250, 43
	v_cmp_eq_u32_e64 s[6:7], 0, v216
	v_readlane_b32 s65, v250, 1
	v_lshl_add_u64 v[234:235], v[234:235], 1, s[50:51]
	v_lshl_add_u64 v[234:235], v[196:197], 1, v[234:235]
	v_readlane_b32 s66, v250, 2
	v_readlane_b32 s67, v250, 3
	v_readlane_b32 s68, v250, 4
	v_readlane_b32 s69, v250, 5
	s_waitcnt vmcnt(12)
	v_pk_fma_f32 v[126:127], s[48:49], v[126:127], v[220:221]
	v_pk_fma_f32 v[124:125], s[12:13], v[124:125], v[218:219]
	v_pk_fma_f32 v[120:121], s[12:13], v[120:121], v[222:223]
	v_pk_fma_f32 v[218:219], s[12:13], v[112:113], v[230:231]
	v_mul_f32_e32 v112, v125, v125
	v_mul_f32_e32 v113, v127, v127
	v_pk_fma_f32 v[118:119], s[48:49], v[118:119], v[228:229]
	v_pk_fma_f32 v[116:117], s[12:13], v[116:117], v[226:227]
	v_pk_fma_f32 v[220:221], s[48:49], v[114:115], v[232:233]
	v_mul_f32_e32 v114, v121, v121
	v_fmac_f32_e32 v112, v124, v124
	v_fmac_f32_e32 v113, v126, v126
	v_pk_fma_f32 v[122:123], s[48:49], v[122:123], v[224:225]
	global_store_dwordx4 v[236:237], v[124:127], off
	global_store_dwordx4 v[236:237], v[120:123], off offset:16
	v_cvt_pk_bf16_f32 v222, v124, v125
	v_cvt_pk_bf16_f32 v223, v126, v127
	v_cvt_pk_bf16_f32 v224, v120, v121
	v_fmac_f32_e32 v114, v120, v120
	v_add_f32_e32 v112, v112, v113
	v_mul_f32_e32 v121, v117, v117
	v_mul_f32_e32 v113, v119, v119
	v_fmac_f32_e32 v121, v116, v116
	v_add_f32_e32 v112, v114, v112
	v_fmac_f32_e32 v113, v118, v118
	v_mul_f32_e32 v114, v219, v219
	v_add_f32_e32 v113, v121, v113
	v_fmac_f32_e32 v114, v218, v218
	v_mul_f32_e32 v115, v123, v123
	v_add_f32_e32 v113, v114, v113
	v_mul_f32_e32 v114, v221, v221
	v_fmac_f32_e32 v115, v122, v122
	v_fmac_f32_e32 v114, v220, v220
	v_add_f32_e32 v112, v115, v112
	v_add_f32_e32 v113, v114, v113
	v_add_f32_e32 v112, v112, v113
	v_cndmask_b32_e32 v113, v203, v209, vcc
	v_lshlrev_b32_e32 v114, 2, v113
	ds_bpermute_b32 v113, v114, v112
	v_cmp_lt_i32_e32 vcc, v210, v204
	v_cvt_pk_bf16_f32 v225, v122, v123
	global_store_dwordx4 v[234:235], v[222:225], off
	global_store_dwordx4 v[236:237], v[116:119], off offset:512
	global_store_dwordx4 v[236:237], v[218:221], off offset:528
	s_waitcnt lgkmcnt(0)
	v_add_f32_e32 v112, v112, v113
	v_cndmask_b32_e32 v113, v203, v210, vcc
	v_lshlrev_b32_e32 v115, 2, v113
	ds_bpermute_b32 v113, v115, v112
	v_cvt_pk_bf16_f32 v116, v116, v117
	v_cvt_pk_bf16_f32 v117, v118, v119
	v_cvt_pk_bf16_f32 v118, v218, v219
	v_cvt_pk_bf16_f32 v119, v220, v221
	global_store_dwordx4 v[234:235], v[116:119], off offset:256
	s_and_saveexec_b64 s[50:51], s[6:7]
	s_cbranch_execz .LBB0_1015
	s_lshl_b32 s53, s52, 2
	s_add_i32 s53, s53, 0
	v_lshl_add_u32 v116, v198, 4, s53
	v_add_u32_e32 v116, 0x20000, v116
	s_waitcnt lgkmcnt(0)
	v_add_f32_e32 v112, v112, v113
	ds_write_b32 v116, v112
.LBB0_1015:
	s_or_b64 exec, exec, s[50:51]
	v_or_b32_e32 v112, 16, v198
	s_waitcnt lgkmcnt(0)
	v_ashrrev_i32_e32 v113, 31, v112
	v_lshlrev_b64 v[116:117], 10, v[112:113]
	v_readlane_b32 s64, v250, 0
	v_lshl_add_u64 v[120:121], v[116:117], 0, s[36:37]
	v_readlane_b32 s70, v250, 6
	v_readlane_b32 s71, v250, 7
	s_waitcnt vmcnt(14)
	v_pk_fma_f32 v[110:111], s[48:49], v[110:111], v[174:175]
	v_pk_fma_f32 v[108:109], s[12:13], v[108:109], v[172:173]
	v_lshl_add_u64 v[116:117], v[120:121], 2, s[70:71]
	v_lshl_add_u64 v[122:123], v[196:197], 2, v[116:117]
	v_pk_fma_f32 v[106:107], s[48:49], v[106:107], v[170:171]
	v_pk_fma_f32 v[104:105], s[12:13], v[104:105], v[168:169]
	global_store_dwordx4 v[122:123], v[108:111], off
	global_store_dwordx4 v[122:123], v[104:107], off offset:16
	v_cvt_pk_bf16_f32 v116, v108, v109
	v_cvt_pk_bf16_f32 v117, v110, v111
	v_cvt_pk_bf16_f32 v118, v104, v105
	v_pk_fma_f32 v[102:103], s[48:49], v[102:103], v[166:167]
	v_mul_f32_e32 v109, v109, v109
	v_fmac_f32_e32 v109, v108, v108
	v_mul_f32_e32 v108, v111, v111
	v_fmac_f32_e32 v108, v110, v110
	v_mul_f32_e32 v105, v105, v105
	v_add_f32_e32 v108, v109, v108
	v_fmac_f32_e32 v105, v104, v104
	v_add_f32_e32 v104, v105, v108
	v_mul_f32_e32 v105, v107, v107
	v_fmac_f32_e32 v105, v106, v106
	v_pk_fma_f32 v[100:101], s[12:13], v[100:101], v[164:165]
	v_add_f32_e32 v108, v105, v104
	v_pk_fma_f32 v[104:105], s[12:13], v[96:97], v[160:161]
	v_mul_f32_e32 v96, v101, v101
	v_mul_f32_e32 v97, v103, v103
	v_fmac_f32_e32 v96, v100, v100
	v_fmac_f32_e32 v97, v102, v102
	v_add_f32_e32 v96, v96, v97
	v_mul_f32_e32 v97, v105, v105
	v_cvt_pk_bf16_f32 v119, v106, v107
	v_pk_fma_f32 v[106:107], s[48:49], v[98:99], v[162:163]
	v_fmac_f32_e32 v97, v104, v104
	v_add_f32_e32 v96, v97, v96
	v_mul_f32_e32 v97, v107, v107
	v_fmac_f32_e32 v97, v106, v106
	v_add_f32_e32 v96, v97, v96
	v_add_f32_e32 v96, v108, v96
	ds_bpermute_b32 v97, v114, v96
	v_readlane_b32 s50, v250, 42
	v_readlane_b32 s51, v250, 43
	v_readlane_b32 s65, v250, 1
	v_readlane_b32 s66, v250, 2
	s_waitcnt lgkmcnt(0)
	v_add_f32_e32 v96, v96, v97
	ds_bpermute_b32 v97, v115, v96
	v_lshl_add_u64 v[120:121], v[120:121], 1, s[50:51]
	v_lshl_add_u64 v[120:121], v[196:197], 1, v[120:121]
	v_readlane_b32 s67, v250, 3
	v_readlane_b32 s68, v250, 4
	v_readlane_b32 s69, v250, 5
	global_store_dwordx4 v[120:121], v[116:119], off
	global_store_dwordx4 v[122:123], v[100:103], off offset:512
	global_store_dwordx4 v[122:123], v[104:107], off offset:528
	v_cvt_pk_bf16_f32 v98, v100, v101
	v_cvt_pk_bf16_f32 v99, v102, v103
	s_nop 0
	v_cvt_pk_bf16_f32 v100, v104, v105
	v_cvt_pk_bf16_f32 v101, v106, v107
	global_store_dwordx4 v[120:121], v[98:101], off offset:256
	s_and_saveexec_b64 s[50:51], s[6:7]
	s_cbranch_execz .LBB0_1017
	s_lshl_b32 s53, s52, 2
	s_add_i32 s53, s53, 0
	v_lshl_add_u32 v98, v112, 4, s53
	v_add_u32_e32 v98, 0x20000, v98
	s_waitcnt lgkmcnt(0)
	v_add_f32_e32 v96, v96, v97
	ds_write_b32 v98, v96
.LBB0_1017:
	s_or_b64 exec, exec, s[50:51]
	v_or_b32_e32 v96, 32, v198
	s_waitcnt lgkmcnt(0)
	v_ashrrev_i32_e32 v97, 31, v96
	v_lshlrev_b64 v[98:99], 10, v[96:97]
	v_readlane_b32 s64, v250, 0
	v_lshl_add_u64 v[102:103], v[98:99], 0, s[36:37]
	v_readlane_b32 s70, v250, 6
	v_readlane_b32 s71, v250, 7
	s_waitcnt vmcnt(16)
	v_pk_fma_f32 v[94:95], s[48:49], v[94:95], v[158:159]
	v_pk_fma_f32 v[92:93], s[12:13], v[92:93], v[156:157]
	v_lshl_add_u64 v[98:99], v[102:103], 2, s[70:71]
	v_lshl_add_u64 v[104:105], v[196:197], 2, v[98:99]
	v_pk_fma_f32 v[90:91], s[48:49], v[90:91], v[154:155]
	v_pk_fma_f32 v[88:89], s[12:13], v[88:89], v[152:153]
	global_store_dwordx4 v[104:105], v[92:95], off
	global_store_dwordx4 v[104:105], v[88:91], off offset:16
	v_cvt_pk_bf16_f32 v98, v92, v93
	v_cvt_pk_bf16_f32 v99, v94, v95
	v_cvt_pk_bf16_f32 v100, v88, v89
	v_pk_fma_f32 v[86:87], s[48:49], v[86:87], v[150:151]
	v_mul_f32_e32 v93, v93, v93
	v_fmac_f32_e32 v93, v92, v92
	v_mul_f32_e32 v92, v95, v95
	v_fmac_f32_e32 v92, v94, v94
	v_mul_f32_e32 v89, v89, v89
	v_add_f32_e32 v92, v93, v92
	v_fmac_f32_e32 v89, v88, v88
	v_add_f32_e32 v88, v89, v92
	v_mul_f32_e32 v89, v91, v91
	v_fmac_f32_e32 v89, v90, v90
	v_pk_fma_f32 v[84:85], s[12:13], v[84:85], v[148:149]
	v_add_f32_e32 v92, v89, v88
	v_pk_fma_f32 v[88:89], s[12:13], v[80:81], v[144:145]
	v_mul_f32_e32 v80, v85, v85
	v_mul_f32_e32 v81, v87, v87
	v_fmac_f32_e32 v80, v84, v84
	v_fmac_f32_e32 v81, v86, v86
	v_add_f32_e32 v80, v80, v81
	v_mul_f32_e32 v81, v89, v89
	v_cvt_pk_bf16_f32 v101, v90, v91
	v_pk_fma_f32 v[90:91], s[48:49], v[82:83], v[146:147]
	v_fmac_f32_e32 v81, v88, v88
	v_add_f32_e32 v80, v81, v80
	v_mul_f32_e32 v81, v91, v91
	v_fmac_f32_e32 v81, v90, v90
	v_add_f32_e32 v80, v81, v80
	v_add_f32_e32 v80, v92, v80
	ds_bpermute_b32 v81, v114, v80
	v_readlane_b32 s50, v250, 42
	v_readlane_b32 s51, v250, 43
	v_readlane_b32 s65, v250, 1
	v_readlane_b32 s66, v250, 2
	s_waitcnt lgkmcnt(0)
	v_add_f32_e32 v80, v80, v81
	ds_bpermute_b32 v81, v115, v80
	v_lshl_add_u64 v[102:103], v[102:103], 1, s[50:51]
	v_lshl_add_u64 v[102:103], v[196:197], 1, v[102:103]
	v_readlane_b32 s67, v250, 3
	v_readlane_b32 s68, v250, 4
	v_readlane_b32 s69, v250, 5
	global_store_dwordx4 v[102:103], v[98:101], off
	global_store_dwordx4 v[104:105], v[84:87], off offset:512
	global_store_dwordx4 v[104:105], v[88:91], off offset:528
	v_cvt_pk_bf16_f32 v82, v84, v85
	v_cvt_pk_bf16_f32 v83, v86, v87
	s_nop 0
	v_cvt_pk_bf16_f32 v84, v88, v89
	v_cvt_pk_bf16_f32 v85, v90, v91
	global_store_dwordx4 v[102:103], v[82:85], off offset:256
	s_and_saveexec_b64 s[50:51], s[6:7]
	s_cbranch_execz .LBB0_1019
	s_lshl_b32 s53, s52, 2
	s_add_i32 s53, s53, 0
	v_lshl_add_u32 v82, v96, 4, s53
	v_add_u32_e32 v82, 0x20000, v82
	s_waitcnt lgkmcnt(0)
	v_add_f32_e32 v80, v80, v81
	ds_write_b32 v82, v80
.LBB0_1019:
	s_or_b64 exec, exec, s[50:51]
	v_or_b32_e32 v80, 48, v198
	s_waitcnt lgkmcnt(0)
	v_ashrrev_i32_e32 v81, 31, v80
	v_lshlrev_b64 v[82:83], 10, v[80:81]
	v_readlane_b32 s64, v250, 0
	v_lshl_add_u64 v[86:87], v[82:83], 0, s[36:37]
	v_readlane_b32 s70, v250, 6
	v_readlane_b32 s71, v250, 7
	s_waitcnt vmcnt(18)
	v_pk_fma_f32 v[78:79], s[48:49], v[78:79], v[142:143]
	v_pk_fma_f32 v[76:77], s[12:13], v[76:77], v[140:141]
	v_lshl_add_u64 v[82:83], v[86:87], 2, s[70:71]
	v_lshl_add_u64 v[88:89], v[196:197], 2, v[82:83]
	v_pk_fma_f32 v[74:75], s[48:49], v[74:75], v[138:139]
	v_pk_fma_f32 v[72:73], s[12:13], v[72:73], v[136:137]
	global_store_dwordx4 v[88:89], v[76:79], off
	global_store_dwordx4 v[88:89], v[72:75], off offset:16
	v_cvt_pk_bf16_f32 v82, v76, v77
	v_cvt_pk_bf16_f32 v83, v78, v79
	v_cvt_pk_bf16_f32 v84, v72, v73
	v_pk_fma_f32 v[70:71], s[48:49], v[70:71], v[134:135]
	v_mul_f32_e32 v77, v77, v77
	v_fmac_f32_e32 v77, v76, v76
	v_mul_f32_e32 v76, v79, v79
	v_fmac_f32_e32 v76, v78, v78
	v_mul_f32_e32 v73, v73, v73
	v_add_f32_e32 v76, v77, v76
	v_fmac_f32_e32 v73, v72, v72
	v_add_f32_e32 v72, v73, v76
	v_mul_f32_e32 v73, v75, v75
	v_fmac_f32_e32 v73, v74, v74
	v_pk_fma_f32 v[68:69], s[12:13], v[68:69], v[132:133]
	v_add_f32_e32 v76, v73, v72
	v_pk_fma_f32 v[72:73], s[12:13], v[64:65], v[128:129]
	v_mul_f32_e32 v64, v69, v69
	v_mul_f32_e32 v65, v71, v71
	v_fmac_f32_e32 v64, v68, v68
	v_fmac_f32_e32 v65, v70, v70
	v_add_f32_e32 v64, v64, v65
	v_mul_f32_e32 v65, v73, v73
	v_cvt_pk_bf16_f32 v85, v74, v75
	v_pk_fma_f32 v[74:75], s[48:49], v[66:67], v[130:131]
	v_fmac_f32_e32 v65, v72, v72
	v_add_f32_e32 v64, v65, v64
	v_mul_f32_e32 v65, v75, v75
	v_fmac_f32_e32 v65, v74, v74
	v_add_f32_e32 v64, v65, v64
	v_add_f32_e32 v64, v76, v64
	ds_bpermute_b32 v65, v114, v64
	v_readlane_b32 s50, v250, 42
	v_readlane_b32 s51, v250, 43
	v_readlane_b32 s65, v250, 1
	v_readlane_b32 s66, v250, 2
	s_waitcnt lgkmcnt(0)
	v_add_f32_e32 v64, v64, v65
	ds_bpermute_b32 v65, v115, v64
	v_lshl_add_u64 v[86:87], v[86:87], 1, s[50:51]
	v_lshl_add_u64 v[86:87], v[196:197], 1, v[86:87]
	v_readlane_b32 s67, v250, 3
	v_readlane_b32 s68, v250, 4
	v_readlane_b32 s69, v250, 5
	global_store_dwordx4 v[86:87], v[82:85], off
	global_store_dwordx4 v[88:89], v[68:71], off offset:512
	global_store_dwordx4 v[88:89], v[72:75], off offset:528
	v_cvt_pk_bf16_f32 v66, v68, v69
	v_cvt_pk_bf16_f32 v67, v70, v71
	s_nop 0
	v_cvt_pk_bf16_f32 v68, v72, v73
	v_cvt_pk_bf16_f32 v69, v74, v75
	global_store_dwordx4 v[86:87], v[66:69], off offset:256
	s_and_saveexec_b64 s[50:51], s[6:7]
	s_cbranch_execz .LBB0_1021
	s_lshl_b32 s53, s52, 2
	s_add_i32 s53, s53, 0
	v_lshl_add_u32 v66, v80, 4, s53
	v_add_u32_e32 v66, 0x20000, v66
	s_waitcnt lgkmcnt(0)
	v_add_f32_e32 v64, v64, v65
	ds_write_b32 v66, v64
